# MoBA steps >= 1: first item's query lookup and Q loads hoisted above the step barrier and K/V LDS stores (store waits bumped by 2)
# speedup vs baseline: 1.0116x; 1.0116x over previous
; #define MB_LOAD(nn) do { _Pragma("unroll") for (int i = 0; i < 4; ++i) { const int cidx = tid + 512 * i, row = cidx >> 3, ch = cidx & 7; \
;         const bf16* src = Zb + (size_t)((nn) * 256 + row) * ZC + h * 64 + ch * 8; kreg[i] = *(const v4u*)(src + KC); vreg[i] = *(const v4u*)(src + VC); } } while (0)
; #define MB_STORE() do { _Pragma("unroll") for (int i = 0; i < 4; ++i) { const int cidx = tid + 512 * i, row = cidx >> 3, ch = cidx & 7; \
;         *(LAS v4u*)(lds + MB_K + row * 144 + ch * 16) = kreg[i]; *(LAS v4u*)(lds + MB_V + row * 144 + ch * 16) = vreg[i]; } } while (0)
; #define MB_QID(st, k, qid, valid) do { if ((st) == 0) { const int it_ = (k) ? 15 - C.wave : C.wave; qid = 16 * it_ + i16; valid = true; } \
;         else { const int pos_ = 16 * (C.wave + 8 * (k)) + i16; valid = pos_ < cnt[(st) - 1]; qid = lists[((st) - 1) * 256 + (valid ? pos_ : 0)]; } } while (0)
; #define MB_QLOAD(qid, d0, d1) do { const bf16* qp_ = Zb + (size_t)(qb * 256 + (qid)) * ZC + QC + h * 64 + 8 * (lane >> 4); d0 = *(const bf16x8*)qp_; d1 = *(const bf16x8*)(qp_ + 32); } while (0)
; __device__ __forceinline__ void moba_unit(const Ctx& C, int unit, const float* KM) {
;     ...
;     MB_LOAD(qb);
;     __syncthreads();
;     for (int step = 0; step <= qb; ++step) {
;         __syncthreads();
;         MB_STORE();
;         __syncthreads();
;         if (step < qb) MB_LOAD(step);
; #pragma unroll 1
;         for (int k = 0; MB_EXISTS(step, k); ++k) {
;             int cqid; bool cvalid; bf16x8 cq0, cq1;
;             MB_QID(step, k, cqid, cvalid); MB_QLOAD(cqid, cq0, cq1);
.LBB0_487:
	s_cmp_eq_u32 s52, 0
	s_cbranch_scc1 .Lqp_step0
	s_lshl_b32 s22, s52, 2
	v_mov_b32_e32 v33, s22
	ds_read_b32 v33, v33 offset:60
	s_add_i32 s22, s52, -1
	s_lshl_b32 s22, s22, 8
	s_waitcnt lgkmcnt(0)
	v_cmp_lt_i32_e64 s[100:101], v217, v33
	s_nop 1
	v_cndmask_b32_e64 v33, 0, v217, s[100:101]
	v_add_u32_e32 v33, s22, v33
	ds_read_u8 v221, v33 offset:3072
	s_waitcnt lgkmcnt(0)
	v_add_u32_e32 v34, s75, v221
	v_mov_b64_e32 v[32:33], s[66:67]
	v_mad_i64_i32 v[32:33], s[22:23], v34, s33, v[32:33]
	v_lshl_add_u64 v[32:33], v[32:33], 0, s[36:37]
	v_lshl_add_u64 v[32:33], v[32:33], 0, v[192:193]
	v_lshl_add_u64 v[34:35], v[32:33], 0, s[88:89]
	v_add_co_u32_e32 v32, vcc, 0x1000, v32
	s_nop 1
	v_addc_co_u32_e32 v33, vcc, 0, v33, vcc
	global_load_dwordx4 v[96:99], v[32:33], off offset:2560
	global_load_dwordx4 v[100:103], v[34:35], off offset:64
	v_add_u32_e32 v32, v206, v213
	s_barrier
	s_waitcnt vmcnt(9)
	ds_write_b128 v32, v[0:3]
	v_add_u32_e32 v32, v207, v213
	s_waitcnt vmcnt(8)
	ds_write_b128 v32, v[4:7]
	v_add_u32_e32 v32, v206, v214
	s_waitcnt vmcnt(7)
	ds_write_b128 v32, v[8:11]
	v_add_u32_e32 v32, v207, v214
	s_waitcnt vmcnt(6)
	ds_write_b128 v32, v[12:15]
	v_add_u32_e32 v32, v206, v215
	s_waitcnt vmcnt(5)
	ds_write_b128 v32, v[16:19]
	v_add_u32_e32 v32, v207, v215
	s_waitcnt vmcnt(4)
	ds_write_b128 v32, v[20:23]
	v_add_u32_e32 v32, v206, v216
	s_waitcnt vmcnt(3)
	ds_write_b128 v32, v[24:27]
	v_add_u32_e32 v32, v207, v216
	s_cmp_ge_i32 s52, s70
	s_waitcnt vmcnt(2)
	ds_write_b128 v32, v[28:31]
	s_waitcnt lgkmcnt(0)
	s_barrier
	s_branch .LBB0_489

; #define MB_LOAD(nn) do { _Pragma("unroll") for (int i = 0; i < 4; ++i) { const int cidx = tid + 512 * i, row = cidx >> 3, ch = cidx & 7; \
;         const bf16* src = Zb + (size_t)((nn) * 256 + row) * ZC + h * 64 + ch * 8; kreg[i] = *(const v4u*)(src + KC); vreg[i] = *(const v4u*)(src + VC); } } while (0)
; #define MB_STORE() do { _Pragma("unroll") for (int i = 0; i < 4; ++i) { const int cidx = tid + 512 * i, row = cidx >> 3, ch = cidx & 7; \
;         *(LAS v4u*)(lds + MB_K + row * 144 + ch * 16) = kreg[i]; *(LAS v4u*)(lds + MB_V + row * 144 + ch * 16) = vreg[i]; } } while (0)
; #define MB_QID(st, k, qid, valid) do { if ((st) == 0) { const int it_ = (k) ? 15 - C.wave : C.wave; qid = 16 * it_ + i16; valid = true; } \
;         else { const int pos_ = 16 * (C.wave + 8 * (k)) + i16; valid = pos_ < cnt[(st) - 1]; qid = lists[((st) - 1) * 256 + (valid ? pos_ : 0)]; } } while (0)
; #define MB_QLOAD(qid, d0, d1) do { const bf16* qp_ = Zb + (size_t)(qb * 256 + (qid)) * ZC + QC + h * 64 + 8 * (lane >> 4); d0 = *(const bf16x8*)qp_; d1 = *(const bf16x8*)(qp_ + 32); } while (0)
; __device__ __forceinline__ void moba_unit(const Ctx& C, int unit, const float* KM) {
;     ...
;     MB_LOAD(qb);
;     __syncthreads();
;     for (int step = 0; step <= qb; ++step) {
;         __syncthreads();
;         MB_STORE();
;         __syncthreads();
;         if (step < qb) MB_LOAD(step);
; #pragma unroll 1
;         for (int k = 0; MB_EXISTS(step, k); ++k) {
;             int cqid; bool cvalid; bf16x8 cq0, cq1;
;             MB_QID(step, k, cqid, cvalid); MB_QLOAD(cqid, cq0, cq1);
.LBB0_496:
	s_mov_b64 s[42:43], -1
	s_and_b64 vcc, exec, s[48:49]
	s_cbranch_vccz .LBB0_498
	s_cmp_lg_u32 s55, 0
	s_cbranch_scc1 .Lqp_normal
	s_mov_b64 s[40:41], s[100:101]
	s_mov_b64 s[42:43], -1
	s_branch .Lqp_have_q
.Lqp_normal:
	v_mov_b32_e32 v32, s20
	ds_read_b32 v32, v32 offset:60
	s_mov_b64 s[42:43], 0
	s_waitcnt lgkmcnt(0)
	v_cmp_lt_i32_e64 s[40:41], v220, v32
	s_nop 1
	v_cndmask_b32_e64 v32, 0, v220, s[40:41]
	v_add_u32_e32 v32, v219, v32
	ds_read_u8 v221, v32 offset:3072

; #define LAS __attribute__((address_space(3)))
; #define SBAR() __builtin_amdgcn_sched_barrier(0)
; #define SBAR() __builtin_amdgcn_sched_barrier(0)
; #define MB_LOAD(nn) do { _Pragma("unroll") for (int i = 0; i < 4; ++i) { const int cidx = tid + 512 * i, row = cidx >> 3, ch = cidx & 7; \
;         const bf16* src = Zb + (size_t)((nn) * 256 + row) * ZC + h * 64 + ch * 8; kreg[i] = *(const v4u*)(src + KC); vreg[i] = *(const v4u*)(src + VC); } } while (0)
; #define MB_STORE() do { _Pragma("unroll") for (int i = 0; i < 4; ++i) { const int cidx = tid + 512 * i, row = cidx >> 3, ch = cidx & 7; \
;         *(LAS v4u*)(lds + MB_K + row * 144 + ch * 16) = kreg[i]; *(LAS v4u*)(lds + MB_V + row * 144 + ch * 16) = vreg[i]; } } while (0)
; #define MB_QID(st, k, qid, valid) do { if ((st) == 0) { const int it_ = (k) ? 15 - C.wave : C.wave; qid = 16 * it_ + i16; valid = true; } \
;         else { const int pos_ = 16 * (C.wave + 8 * (k)) + i16; valid = pos_ < cnt[(st) - 1]; qid = lists[((st) - 1) * 256 + (valid ? pos_ : 0)]; } } while (0)
; #define MB_QLOAD(qid, d0, d1) do { const bf16* qp_ = Zb + (size_t)(qb * 256 + (qid)) * ZC + QC + h * 64 + 8 * (lane >> 4); d0 = *(const bf16x8*)qp_; d1 = *(const bf16x8*)(qp_ + 32); } while (0)
; template <bool OWN>
; __device__ __forceinline__ void moba_item(const bf16x8 q0, const bf16x8 q1, LAS unsigned char* lds, int lane, int qb, int n, int qid, bool valid, int smax) {
;     ...
;         bf16x8 kf[4][2];
; #pragma unroll
;         for (int t = 0; t < 4; ++t) { const LAS unsigned char* kp = kbase + (64 * sp + 32 * (t >> 1) + 16 * (t & 1)) * 144; kf[t][0] = *(const LAS bf16x8*)kp; kf[t][1] = *(const LAS bf16x8*)(kp + 64); }
;         SBAR();
; __device__ __forceinline__ void moba_unit(const Ctx& C, int unit, const float* KM) {
;     ...
;     MB_LOAD(qb);
;     __syncthreads();
;     for (int step = 0; step <= qb; ++step) {
;         __syncthreads();
;         MB_STORE();
;         __syncthreads();
;         if (step < qb) MB_LOAD(step);
; #pragma unroll 1
;         for (int k = 0; MB_EXISTS(step, k); ++k) {
;             int cqid; bool cvalid; bf16x8 cq0, cq1;
;             MB_QID(step, k, cqid, cvalid); MB_QLOAD(cqid, cq0, cq1);
.LBB0_500:
	s_waitcnt lgkmcnt(0)
	v_add_u32_e32 v34, s75, v221
	v_mov_b64_e32 v[32:33], s[66:67]
	v_mad_i64_i32 v[32:33], s[22:23], v34, s33, v[32:33]
	v_lshl_add_u64 v[32:33], v[32:33], 0, s[36:37]
	v_lshl_add_u64 v[32:33], v[32:33], 0, v[192:193]
	v_lshl_add_u64 v[34:35], v[32:33], 0, s[88:89]
	v_add_co_u32_e32 v32, vcc, 0x1000, v32
	s_mov_b64 s[42:43], -1
	s_nop 0
	v_addc_co_u32_e32 v33, vcc, 0, v33, vcc
	global_load_dwordx4 v[96:99], v[32:33], off offset:2560
	global_load_dwordx4 v[100:103], v[34:35], off offset:64
.Lqp_have_q:
	s_cmp_lg_u32 s55, 0
	s_cbranch_scc1 .Lmb_pf_skip_a
	s_cmp_ge_i32 s52, s70
	s_cbranch_scc1 .Lmb_pf_skip_a
	v_lshl_add_u32 v0, s52, 8, v188
	v_mad_i64_i32 v[0:1], s[22:23], v0, s33, v[104:105]
	v_add_co_u32_e32 v2, vcc, 0x1000, v0
	v_lshl_add_u32 v8, s52, 8, v189
	s_nop 0
	v_addc_co_u32_e32 v3, vcc, 0, v1, vcc
	v_add_co_u32_e32 v4, vcc, 0x2000, v0
	v_mad_i64_i32 v[8:9], s[22:23], v8, s33, v[104:105]
	s_nop 0
	v_addc_co_u32_e32 v5, vcc, 0, v1, vcc
	v_add_co_u32_e32 v10, vcc, 0x1000, v8
	v_lshl_add_u32 v16, s52, 8, v190
	s_nop 0
	v_addc_co_u32_e32 v11, vcc, 0, v9, vcc
	v_add_co_u32_e32 v12, vcc, 0x2000, v8
	v_mad_i64_i32 v[16:17], s[22:23], v16, s33, v[104:105]
	s_nop 0
	v_addc_co_u32_e32 v13, vcc, 0, v9, vcc
	v_add_co_u32_e32 v18, vcc, 0x1000, v16
	v_lshl_add_u32 v24, s52, 8, v191
	s_nop 0
	v_addc_co_u32_e32 v19, vcc, 0, v17, vcc
	v_add_co_u32_e32 v20, vcc, 0x2000, v16
	v_mad_i64_i32 v[24:25], s[22:23], v24, s33, v[104:105]
	s_nop 0
	v_addc_co_u32_e32 v21, vcc, 0, v17, vcc
	v_add_co_u32_e32 v26, vcc, 0x1000, v24
	global_load_dwordx4 v[0:3], v[2:3], off offset:3584
	s_nop 0
	global_load_dwordx4 v[4:7], v[4:5], off offset:512
	v_addc_co_u32_e32 v27, vcc, 0, v25, vcc
	v_add_co_u32_e32 v28, vcc, 0x2000, v24
	global_load_dwordx4 v[8:11], v[10:11], off offset:3584
	s_nop 0
	global_load_dwordx4 v[12:15], v[12:13], off offset:512
	v_addc_co_u32_e32 v29, vcc, 0, v25, vcc
	global_load_dwordx4 v[16:19], v[18:19], off offset:3584
	s_nop 0
	global_load_dwordx4 v[20:23], v[20:21], off offset:512
	s_nop 0
	global_load_dwordx4 v[24:27], v[26:27], off offset:3584
	s_nop 0
	global_load_dwordx4 v[28:31], v[28:29], off offset:512
.Lmb_pf_skip_a:
	s_and_b64 vcc, exec, s[48:49]
	v_sub_u32_e32 v222, v221, v208
	s_cbranch_vccz .LBB0_505
	ds_read_b128 v[32:35], v218
	ds_read_b128 v[36:39], v218 offset:64
	ds_read_b128 v[40:43], v218 offset:2304
	ds_read_b128 v[44:47], v218 offset:2368
	ds_read_b128 v[48:51], v218 offset:4608
	ds_read_b128 v[52:55], v218 offset:4672
	ds_read_b128 v[56:59], v218 offset:6912
	ds_read_b128 v[60:63], v218 offset:6976
	s_cmp_lg_u32 s55, 0
	s_cbranch_scc1 .Lmb_w_all
	s_cmp_ge_i32 s52, s70
	s_cbranch_scc1 .Lmb_w_all
	s_waitcnt vmcnt(8)
	s_branch .Lmb_w_done

; __global__ void __launch_bounds__(512) hybrid_fwd(Params p) {
	.amdhsa_kernel _Z10hybrid_fwd6Params
		.amdhsa_group_segment_fixed_size 0
		.amdhsa_private_segment_fixed_size 0
		.amdhsa_kernarg_size 424
		.amdhsa_user_sgpr_count 2
		.amdhsa_user_sgpr_dispatch_ptr 0
		.amdhsa_user_sgpr_queue_ptr 0
		.amdhsa_user_sgpr_kernarg_segment_ptr 1
		.amdhsa_user_sgpr_dispatch_id 0
		.amdhsa_user_sgpr_kernarg_preload_length 0
		.amdhsa_user_sgpr_kernarg_preload_offset 0
		.amdhsa_user_sgpr_private_segment_size 0
		.amdhsa_uses_dynamic_stack 0
		.amdhsa_enable_private_segment 0
		.amdhsa_system_sgpr_workgroup_id_x 1
		.amdhsa_system_sgpr_workgroup_id_y 0
		.amdhsa_system_sgpr_workgroup_id_z 0
		.amdhsa_system_sgpr_workgroup_info 0
		.amdhsa_system_vgpr_workitem_id 2
		.amdhsa_next_free_vgpr 251
		.amdhsa_next_free_sgpr 102
		.amdhsa_accum_offset 252
		.amdhsa_reserve_vcc 1
		.amdhsa_float_round_mode_32 0
		.amdhsa_float_round_mode_16_64 0
		.amdhsa_float_denorm_mode_32 3
		.amdhsa_float_denorm_mode_16_64 3
		.amdhsa_dx10_clamp 1
		.amdhsa_ieee_mode 1
		.amdhsa_fp16_overflow 0
		.amdhsa_tg_split 0
		.amdhsa_exception_fp_ieee_invalid_op 0
		.amdhsa_exception_fp_denorm_src 0
		.amdhsa_exception_fp_ieee_div_zero 0
		.amdhsa_exception_fp_ieee_overflow 0
		.amdhsa_exception_fp_ieee_underflow 0
		.amdhsa_exception_fp_ieee_inexact 0
		.amdhsa_exception_int_div_zero 0
	.end_amdhsa_kernel

; __global__ void __launch_bounds__(512) hybrid_fwd(Params p) {
amdhsa.kernels:
  - .agpr_count:     0
    .args:
      - .offset:         0
        .size:           168
        .value_kind:     by_value
      - .offset:         168
        .size:           4
        .value_kind:     hidden_block_count_x
      - .offset:         172
        .size:           4
        .value_kind:     hidden_block_count_y
      - .offset:         176
        .size:           4
        .value_kind:     hidden_block_count_z
      - .offset:         180
        .size:           2
        .value_kind:     hidden_group_size_x
      - .offset:         182
        .size:           2
        .value_kind:     hidden_group_size_y
      - .offset:         184
        .size:           2
        .value_kind:     hidden_group_size_z
      - .offset:         186
        .size:           2
        .value_kind:     hidden_remainder_x
      - .offset:         188
        .size:           2
        .value_kind:     hidden_remainder_y
      - .offset:         190
        .size:           2
        .value_kind:     hidden_remainder_z
      - .offset:         208
        .size:           8
        .value_kind:     hidden_global_offset_x
      - .offset:         216
        .size:           8
        .value_kind:     hidden_global_offset_y
      - .offset:         224
        .size:           8
        .value_kind:     hidden_global_offset_z
      - .offset:         232
        .size:           2
        .value_kind:     hidden_grid_dims
      - .offset:         256
        .size:           8
        .value_kind:     hidden_multigrid_sync_arg
      - .offset:         288
        .size:           4
        .value_kind:     hidden_dynamic_lds_size
    .group_segment_fixed_size: 0
    .kernarg_segment_align: 8
    .kernarg_segment_size: 424
    .language:       OpenCL C
    .language_version:
      - 2
      - 0
    .max_flat_workgroup_size: 512
    .name:           _Z10hybrid_fwd6Params
    .private_segment_fixed_size: 0
    .sgpr_count:     108
    .sgpr_spill_count: 227
    .symbol:         _Z10hybrid_fwd6Params.kd
    .uniform_work_group_size: 1
    .uses_dynamic_stack: false
    .vgpr_count:     251
    .vgpr_spill_count: 0
    .wavefront_size: 64
